# speedup vs baseline: 1.1269x; 1.0045x over previous
; __device__ __forceinline__ void phase_attn(const Params& p, char* smraw) {
;     ...
;   for (int item = blockIdx.x; item < 64 * 65; item += gridDim.x) {
;     const int bh = item & 63, qt = item >> 6;
;     const int qbase = qt * 128 + w * 32, qpos = qbase + lc;
;     const u16* qptr = p.qbuf + ((size_t)bh * LP + qpos) * 64;
;     bf16x8 qf[4];
; #pragma unroll
;     for (int ks = 0; ks < 4; ++ks) qf[ks] = *(const bf16x8*)(qptr + ks * 16 + hf * 8);
;     f32x16 o[2];
; #pragma unroll
;     for (int r = 0; r < 16; ++r) { o[0][r] = 0.f; o[1][r] = 0.f; }
;     float carry = 0.f; int done = 0;
;     const u16* kbase = p.kbuf + (size_t)bh * LP * 64;
;     const u16* vbase = p.vT + (size_t)bh * 64 * LP;
;     const int kt_hi = 2 * qt + 1;
;     u32x4 rk[2], rv[2];
;     auto gload = [&](int kt) {
;       const int key0 = kt * 64;
; #pragma unroll
;       for (int cc = 0; cc < 2; ++cc) {
;         const int c = tid + cc * 256, row = c >> 3, ch = c & 7;
;         rk[cc] = *(const u32x4*)(kbase + (size_t)(key0 + row) * 64 + ch * 8);
;         rv[cc] = *(const u32x4*)(vbase + (size_t)row * LP + key0 + ch * 8);
;       }
;     };
;     gload(kt_hi);
.LBB0_259:
	s_sub_i32 s98, 0x103f, s79
	s_ashr_i32 s0, s98, 6
	s_lshl_b32 s68, s0, 7
	s_and_b32 s92, s98, 63
	v_add_u32_e32 v115, s68, v125
	v_or_b32_e32 v116, v115, v105
	s_cmp_lt_i32 s0, 0
	v_mov_b32_e32 v15, 0
	v_mov_b32_e32 v14, 0
	v_mov_b32_e32 v13, 0
	v_mov_b32_e32 v12, 0
	v_mov_b32_e32 v11, 0
	v_mov_b32_e32 v10, 0
	v_mov_b32_e32 v9, 0
	v_mov_b32_e32 v8, 0
	v_mov_b32_e32 v7, 0
	v_mov_b32_e32 v6, 0
	v_mov_b32_e32 v5, 0
	v_mov_b32_e32 v4, 0
	v_mov_b32_e32 v3, 0
	v_mov_b32_e32 v2, 0
	v_mov_b32_e32 v1, 0
	v_mov_b32_e32 v0, 0
	v_mov_b32_e32 v31, 0
	v_mov_b32_e32 v30, 0
	v_mov_b32_e32 v29, 0
	v_mov_b32_e32 v28, 0
	v_mov_b32_e32 v27, 0
	v_mov_b32_e32 v26, 0
	v_mov_b32_e32 v25, 0
	v_mov_b32_e32 v24, 0
	v_mov_b32_e32 v23, 0
	v_mov_b32_e32 v22, 0
	v_mov_b32_e32 v21, 0
	v_mov_b32_e32 v20, 0
	v_mov_b32_e32 v19, 0
	v_mov_b32_e32 v18, 0
	v_mov_b32_e32 v17, 0
	v_mov_b32_e32 v16, 0
	s_cbranch_scc1 .LBB0_278
	v_readlane_b32 s8, v254, 0
	s_mul_i32 s1, s92, 0x104000
	v_readlane_b32 s22, v254, 14
	v_readlane_b32 s9, v254, 1
	v_readlane_b32 s10, v254, 2
	v_readlane_b32 s11, v254, 3
	v_readlane_b32 s12, v254, 4
	v_readlane_b32 s13, v254, 5
	v_readlane_b32 s14, v254, 6
	v_readlane_b32 s15, v254, 7
	v_readlane_b32 s23, v254, 15
	s_add_u32 s6, s22, s1
	s_addc_u32 s7, s23, 0
	v_readlane_b32 s8, v254, 34
	v_readlane_b32 s9, v254, 35
	s_add_u32 s8, s8, s1
	s_mul_i32 s66, s92, 0x2080
	v_ashrrev_i32_e32 v117, 31, v116
	s_addc_u32 s9, s9, 0
	s_lshl_b32 s1, s0, 7
	v_lshl_add_u64 v[4:5], s[66:67], 0, v[116:117]
	v_lshlrev_b64 v[4:5], 7, v[4:5]
	s_or_b32 s66, s1, 64
	v_lshl_add_u64 v[0:1], s[8:9], 0, v[108:109]
	v_lshl_add_u64 v[2:3], s[8:9], 0, v[110:111]
	v_lshl_add_u64 v[4:5], v[112:113], 0, v[4:5]
	s_lshl_b64 s[8:9], s[66:67], 1
	global_load_dwordx4 v[72:75], v[4:5], off offset:96
	global_load_dwordx4 v[76:79], v[4:5], off offset:64
	global_load_dwordx4 v[80:83], v[4:5], off offset:32
	global_load_dwordx4 v[84:87], v[4:5], off
	v_lshl_add_u64 v[4:5], v[2:3], 0, s[8:9]
	v_lshl_add_u64 v[4:5], v[4:5], 0, v[106:107]
	global_load_dwordx4 v[88:91], v[4:5], off
	v_add_u32_e32 v4, s66, v127
	v_ashrrev_i32_e32 v5, 31, v4
	v_lshlrev_b64 v[4:5], 7, v[4:5]
	v_lshl_add_u64 v[4:5], s[6:7], 0, v[4:5]
	v_lshl_add_u64 v[4:5], v[4:5], 0, v[106:107]
	global_load_dwordx4 v[96:99], v[4:5], off
	v_lshl_add_u64 v[4:5], v[0:1], 0, s[8:9]
	v_lshl_add_u64 v[4:5], v[4:5], 0, v[106:107]
	global_load_dwordx4 v[92:95], v[4:5], off
	v_add_u32_e32 v4, s66, v126
	v_ashrrev_i32_e32 v5, 31, v4
	v_lshlrev_b64 v[4:5], 7, v[4:5]
	v_lshl_add_u64 v[4:5], s[6:7], 0, v[4:5]
	v_lshl_add_u64 v[4:5], v[4:5], 0, v[106:107]
	global_load_dwordx4 v[100:103], v[4:5], off
	s_lshl_b32 s66, s0, 1
	s_movk_i32 s0, 0x70
	v_mov_b32_e32 v32, 0
	v_lshl_add_u64 v[118:119], s[6:7], 0, v[106:107]
	v_lshl_add_u64 v[120:121], v[0:1], 0, v[106:107]
	v_lshl_add_u64 v[122:123], v[2:3], 0, v[106:107]
	v_cmp_gt_i32_e64 s[6:7], s0, v116
	s_mov_b32 s93, 0
	v_mov_b32_e32 v33, 0
	v_mov_b32_e32 v16, 0
	v_mov_b32_e32 v17, v32
	v_mov_b32_e32 v18, v32
	v_mov_b32_e32 v19, v32
	v_mov_b32_e32 v20, v32
	v_mov_b32_e32 v21, v32
	v_mov_b32_e32 v22, v32
	v_mov_b32_e32 v23, v32
	v_mov_b32_e32 v24, v32
	v_mov_b32_e32 v25, v32
	v_mov_b32_e32 v26, v32
	v_mov_b32_e32 v27, v32
	v_mov_b32_e32 v28, v32
	v_mov_b32_e32 v29, v32
	v_mov_b32_e32 v30, v32
	v_mov_b32_e32 v31, v32
	v_mov_b32_e32 v0, v32
	v_mov_b32_e32 v1, v32
	v_mov_b32_e32 v2, v32
	v_mov_b32_e32 v3, v32
	v_mov_b32_e32 v4, v32
	v_mov_b32_e32 v5, v32
	v_mov_b32_e32 v6, v32
	v_mov_b32_e32 v7, v32
	v_mov_b32_e32 v8, v32
	v_mov_b32_e32 v9, v32
	v_mov_b32_e32 v10, v32
	v_mov_b32_e32 v11, v32
	v_mov_b32_e32 v12, v32
	v_mov_b32_e32 v13, v32
	v_mov_b32_e32 v14, v32
	v_mov_b32_e32 v15, v32
	v_readlane_b32 s16, v254, 8
	v_readlane_b32 s17, v254, 9
	v_readlane_b32 s18, v254, 10
	v_readlane_b32 s19, v254, 11
	v_readlane_b32 s20, v254, 12
	v_readlane_b32 s21, v254, 13
	v_readlane_b32 s10, v254, 36
	v_readlane_b32 s11, v254, 37
	v_readlane_b32 s12, v254, 38
	v_readlane_b32 s13, v254, 39
	v_readlane_b32 s14, v254, 40
	v_readlane_b32 s15, v254, 41
	s_branch .LBB0_262

; __device__ __forceinline__ void phase_attn(const Params& p, char* smraw) {
;     ...
;     if (qpos >= PADK) {
;       const int b = bh >> 4, hd = bh & 15;
;       const int t = b * L + qpos - PADK;
;       u16* dst = p.ob + (size_t)t * D + hd * 64;
; #pragma unroll
;       for (int db = 0; db < 2; ++db)
; #pragma unroll
;         for (int rg = 0; rg < 4; ++rg) {
;           u32x2 ov;
;           ov[0] = cvtpk(o[db][rg * 4 + 0], o[db][rg * 4 + 1]);
;           ov[1] = cvtpk(o[db][rg * 4 + 2], o[db][rg * 4 + 3]);
;           *(u32x2*)(dst + db * 32 + 8 * rg + 4 * hf) = ov;
;         }
.LBB0_278:
	v_cmp_lt_i32_e32 vcc, s78, v116
	s_and_saveexec_b64 s[0:1], vcc
	s_cbranch_execz .LBB0_258
	s_lshr_b32 s6, s92, 4
	s_mulk_i32 s6, 0x2010
	s_addk_i32 s6, 0xff90
	v_add_u32_e32 v32, s6, v116
	v_mov_b32_e32 v33, v107
	v_readlane_b32 s8, v254, 34
	v_lshlrev_b64 v[32:33], 11, v[32:33]
	v_readlane_b32 s10, v254, 36
	v_readlane_b32 s11, v254, 37
	s_lshl_b32 s6, s98, 7
	s_and_b32 s66, s6, 0x780
	v_lshl_add_u64 v[32:33], s[10:11], 0, v[32:33]
	v_lshl_add_u64 v[32:33], v[32:33], 0, s[66:67]
	v_mov_b32_e32 v115, v107
	v_lshl_add_u64 v[32:33], v[32:33], 0, v[114:115]
	v_cvt_pk_bf16_f32 v16, v16, v17
	v_cvt_pk_bf16_f32 v17, v18, v19
	global_store_dwordx2 v[32:33], v[16:17], off
	v_cvt_pk_bf16_f32 v16, v20, v21
	v_cvt_pk_bf16_f32 v17, v22, v23
	global_store_dwordx2 v[32:33], v[16:17], off offset:16
	v_cvt_pk_bf16_f32 v16, v24, v25
	v_cvt_pk_bf16_f32 v17, v26, v27
	global_store_dwordx2 v[32:33], v[16:17], off offset:32
	v_cvt_pk_bf16_f32 v16, v28, v29
	v_cvt_pk_bf16_f32 v17, v30, v31
	global_store_dwordx2 v[32:33], v[16:17], off offset:48
	v_cvt_pk_bf16_f32 v0, v0, v1
	v_cvt_pk_bf16_f32 v1, v2, v3
	global_store_dwordx2 v[32:33], v[0:1], off offset:64
	v_cvt_pk_bf16_f32 v0, v4, v5
	v_cvt_pk_bf16_f32 v1, v6, v7
	global_store_dwordx2 v[32:33], v[0:1], off offset:80
	v_cvt_pk_bf16_f32 v0, v8, v9
	v_cvt_pk_bf16_f32 v1, v10, v11
	v_readlane_b32 s9, v254, 35
	v_readlane_b32 s12, v254, 38
	v_readlane_b32 s13, v254, 39
	v_readlane_b32 s14, v254, 40
	v_readlane_b32 s15, v254, 41
	global_store_dwordx2 v[32:33], v[0:1], off offset:96
	v_cvt_pk_bf16_f32 v0, v12, v13
	v_cvt_pk_bf16_f32 v1, v14, v15
	global_store_dwordx2 v[32:33], v[0:1], off offset:112
	s_branch .LBB0_258

; __global__ void __launch_bounds__(NTHREADS, 2) mega(Params p) {
;   __shared__ __attribute__((aligned(16))) char smraw[SMEM_BYTES];
	.amdhsa_kernel _Z4mega6Params
		.amdhsa_group_segment_fixed_size 74244
		.amdhsa_private_segment_fixed_size 0
		.amdhsa_kernarg_size 560
		.amdhsa_user_sgpr_count 2
		.amdhsa_user_sgpr_dispatch_ptr 0
		.amdhsa_user_sgpr_queue_ptr 0
		.amdhsa_user_sgpr_kernarg_segment_ptr 1
		.amdhsa_user_sgpr_dispatch_id 0
		.amdhsa_user_sgpr_kernarg_preload_length 0
		.amdhsa_user_sgpr_kernarg_preload_offset 0
		.amdhsa_user_sgpr_private_segment_size 0
		.amdhsa_uses_dynamic_stack 0
		.amdhsa_enable_private_segment 0
		.amdhsa_system_sgpr_workgroup_id_x 1
		.amdhsa_system_sgpr_workgroup_id_y 0
		.amdhsa_system_sgpr_workgroup_id_z 0
		.amdhsa_system_sgpr_workgroup_info 0
		.amdhsa_system_vgpr_workitem_id 2
		.amdhsa_next_free_vgpr 255
		.amdhsa_next_free_sgpr 99
		.amdhsa_accum_offset 256
		.amdhsa_reserve_vcc 1
		.amdhsa_float_round_mode_32 0
		.amdhsa_float_round_mode_16_64 0
		.amdhsa_float_denorm_mode_32 3
		.amdhsa_float_denorm_mode_16_64 3
		.amdhsa_dx10_clamp 1
		.amdhsa_ieee_mode 1
		.amdhsa_fp16_overflow 0
		.amdhsa_tg_split 0
		.amdhsa_exception_fp_ieee_invalid_op 0
		.amdhsa_exception_fp_denorm_src 0
		.amdhsa_exception_fp_ieee_div_zero 0
		.amdhsa_exception_fp_ieee_overflow 0
		.amdhsa_exception_fp_ieee_underflow 0
		.amdhsa_exception_fp_ieee_inexact 0
		.amdhsa_exception_int_div_zero 0
	.end_amdhsa_kernel

; __global__ void __launch_bounds__(NTHREADS, 2) mega(Params p) {
;   __shared__ __attribute__((aligned(16))) char smraw[SMEM_BYTES];
amdhsa.kernels:
  - .agpr_count:     0
    .args:
      - .offset:         0
        .size:           304
        .value_kind:     by_value
      - .offset:         304
        .size:           4
        .value_kind:     hidden_block_count_x
      - .offset:         308
        .size:           4
        .value_kind:     hidden_block_count_y
      - .offset:         312
        .size:           4
        .value_kind:     hidden_block_count_z
      - .offset:         316
        .size:           2
        .value_kind:     hidden_group_size_x
      - .offset:         318
        .size:           2
        .value_kind:     hidden_group_size_y
      - .offset:         320
        .size:           2
        .value_kind:     hidden_group_size_z
      - .offset:         322
        .size:           2
        .value_kind:     hidden_remainder_x
      - .offset:         324
        .size:           2
        .value_kind:     hidden_remainder_y
      - .offset:         326
        .size:           2
        .value_kind:     hidden_remainder_z
      - .offset:         344
        .size:           8
        .value_kind:     hidden_global_offset_x
      - .offset:         352
        .size:           8
        .value_kind:     hidden_global_offset_y
      - .offset:         360
        .size:           8
        .value_kind:     hidden_global_offset_z
      - .offset:         368
        .size:           2
        .value_kind:     hidden_grid_dims
      - .offset:         392
        .size:           8
        .value_kind:     hidden_multigrid_sync_arg
    .group_segment_fixed_size: 74244
    .kernarg_segment_align: 8
    .kernarg_segment_size: 560
    .language:       OpenCL C
    .language_version:
      - 2
      - 0
    .max_flat_workgroup_size: 256
    .name:           _Z4mega6Params
    .private_segment_fixed_size: 0
    .sgpr_count:     105
    .sgpr_spill_count: 60
    .symbol:         _Z4mega6Params.kd
    .uniform_work_group_size: 1
    .uses_dynamic_stack: false
    .vgpr_count:     255
    .vgpr_spill_count: 0
    .wavefront_size: 64
